# software prefetch of the residual tile (hi/lo) for the out-proj and MLP-out epilogues from inside their K-loops: one dword load per load segment in each wave's own iteration
# baseline (speedup 1.0000x reference)
.LBB0_775:
	s_ashr_i32 s15, s14, 31
	s_lshl_b64 s[16:17], s[14:15], 19
	v_readlane_b32 s18, v250, 10
	v_readlane_b32 s19, v250, 11
	s_add_u32 s16, s18, s16
	s_addc_u32 s17, s19, s17
	s_and_b64 s[18:19], s[8:9], exec
	s_cselect_b32 s15, s17, s23
	s_cselect_b32 s51, s16, s22
	s_ashr_i32 s13, s12, 31
	s_lshl_b64 s[18:19], s[12:13], 19
	s_add_u32 s18, s5, s18
	s_addc_u32 s19, s34, s19
	s_and_b64 s[30:31], s[8:9], exec
	s_cselect_b32 s13, s19, s27
	s_cselect_b32 s52, s18, s26
	s_add_u32 s22, s22, 0x40080
	s_addc_u32 s23, s23, 0
	s_add_u32 s53, s26, 0x100
	v_mov_b32_e32 v0, 0
	s_addc_u32 s54, s27, 0
	s_mov_b32 s55, -2
	s_waitcnt lgkmcnt(0)
	v_mov_b32_e32 v1, v0
	v_mov_b32_e32 v2, v0
	v_mov_b32_e32 v3, v0
	v_mov_b32_e32 v4, v0
	v_mov_b32_e32 v5, v0
	v_mov_b32_e32 v6, v0
	v_mov_b32_e32 v7, v0
	v_mov_b32_e32 v16, v0
	v_mov_b32_e32 v17, v0
	v_mov_b32_e32 v18, v0
	v_mov_b32_e32 v19, v0
	v_mov_b32_e32 v20, v0
	v_mov_b32_e32 v21, v0
	v_mov_b32_e32 v22, v0
	v_mov_b32_e32 v23, v0
	v_mov_b32_e32 v32, v0
	v_mov_b32_e32 v33, v0
	v_mov_b32_e32 v34, v0
	v_mov_b32_e32 v35, v0
	v_mov_b32_e32 v36, v0
	v_mov_b32_e32 v37, v0
	v_mov_b32_e32 v38, v0
	v_mov_b32_e32 v39, v0
	v_mov_b32_e32 v48, v0
	v_mov_b32_e32 v49, v0
	v_mov_b32_e32 v50, v0
	v_mov_b32_e32 v51, v0
	v_mov_b32_e32 v52, v0
	v_mov_b32_e32 v53, v0
	v_mov_b32_e32 v54, v0
	v_mov_b32_e32 v55, v0
	v_mov_b32_e32 v8, v0
	v_mov_b32_e32 v9, v0
	v_mov_b32_e32 v10, v0
	v_mov_b32_e32 v11, v0
	v_mov_b32_e32 v12, v0
	v_mov_b32_e32 v13, v0
	v_mov_b32_e32 v14, v0
	v_mov_b32_e32 v15, v0
	v_mov_b32_e32 v24, v0
	v_mov_b32_e32 v25, v0
	v_mov_b32_e32 v26, v0
	v_mov_b32_e32 v27, v0
	v_mov_b32_e32 v28, v0
	v_mov_b32_e32 v29, v0
	v_mov_b32_e32 v30, v0
	v_mov_b32_e32 v31, v0
	v_mov_b32_e32 v40, v0
	v_mov_b32_e32 v41, v0
	v_mov_b32_e32 v42, v0
	v_mov_b32_e32 v43, v0
	v_mov_b32_e32 v44, v0
	v_mov_b32_e32 v45, v0
	v_mov_b32_e32 v46, v0
	v_mov_b32_e32 v47, v0
	v_mov_b32_e32 v56, v0
	v_mov_b32_e32 v57, v0
	v_mov_b32_e32 v58, v0
	v_mov_b32_e32 v59, v0
	v_mov_b32_e32 v60, v0
	v_mov_b32_e32 v61, v0
	v_mov_b32_e32 v62, v0
	v_mov_b32_e32 v63, v0
	v_mov_b32_e32 v64, v0
	v_mov_b32_e32 v65, v0
	v_mov_b32_e32 v66, v0
	v_mov_b32_e32 v67, v0
	v_mov_b32_e32 v68, v0
	v_mov_b32_e32 v69, v0
	v_mov_b32_e32 v70, v0
	v_mov_b32_e32 v71, v0
	v_mov_b32_e32 v80, v0
	v_mov_b32_e32 v81, v0
	v_mov_b32_e32 v82, v0
	v_mov_b32_e32 v83, v0
	v_mov_b32_e32 v84, v0
	v_mov_b32_e32 v85, v0
	v_mov_b32_e32 v86, v0
	v_mov_b32_e32 v87, v0
	v_mov_b32_e32 v96, v0
	v_mov_b32_e32 v97, v0
	v_mov_b32_e32 v98, v0
	v_mov_b32_e32 v99, v0
	v_mov_b32_e32 v100, v0
	v_mov_b32_e32 v101, v0
	v_mov_b32_e32 v102, v0
	v_mov_b32_e32 v103, v0
	v_mov_b32_e32 v112, v0
	v_mov_b32_e32 v113, v0
	v_mov_b32_e32 v114, v0
	v_mov_b32_e32 v115, v0
	v_mov_b32_e32 v116, v0
	v_mov_b32_e32 v117, v0
	v_mov_b32_e32 v118, v0
	v_mov_b32_e32 v119, v0
	v_mov_b32_e32 v72, v0
	v_mov_b32_e32 v73, v0
	v_mov_b32_e32 v74, v0
	v_mov_b32_e32 v75, v0
	v_mov_b32_e32 v76, v0
	v_mov_b32_e32 v77, v0
	v_mov_b32_e32 v78, v0
	v_mov_b32_e32 v79, v0
	v_mov_b32_e32 v88, v0
	v_mov_b32_e32 v89, v0
	v_mov_b32_e32 v90, v0
	v_mov_b32_e32 v91, v0
	v_mov_b32_e32 v92, v0
	v_mov_b32_e32 v93, v0
	v_mov_b32_e32 v94, v0
	v_mov_b32_e32 v95, v0
	v_mov_b32_e32 v104, v0
	v_mov_b32_e32 v105, v0
	v_mov_b32_e32 v106, v0
	v_mov_b32_e32 v107, v0
	v_mov_b32_e32 v108, v0
	v_mov_b32_e32 v109, v0
	v_mov_b32_e32 v110, v0
	v_mov_b32_e32 v111, v0
	v_mov_b32_e32 v120, v0
	v_mov_b32_e32 v121, v0
	v_mov_b32_e32 v122, v0
	v_mov_b32_e32 v123, v0
	v_mov_b32_e32 v124, v0
	v_mov_b32_e32 v125, v0
	v_mov_b32_e32 v126, v0
	v_mov_b32_e32 v127, v0
	v_lshrrev_b32_e32 v251, 1, v216
	v_lshl_add_u32 v251, s24, 8, v251
	v_lshlrev_b32_e32 v251, 11, v251
	v_and_b32_e32 v254, 1, v216
	v_lshl_add_u32 v251, v254, 8, v251
	v_lshl_add_u32 v254, s50, 9, v251
	v_mov_b32_e32 v255, 0
	v_readlane_b32 vcc_lo, v247, 5
	v_readlane_b32 vcc_hi, v247, 6
	s_nop 1
	v_lshl_add_u64 v[252:253], vcc, 0, v[254:255]
	v_readlane_b32 vcc_lo, v249, 0
	v_readlane_b32 vcc_hi, v249, 1
	s_nop 1
	v_lshl_add_u64 v[254:255], vcc, 0, v[254:255]
	v_readfirstlane_b32 vcc_lo, v216
	s_nop 3
	s_lshr_b32 vcc_lo, vcc_lo, 6
	s_lshl_b32 vcc_lo, vcc_lo, 1
.LBB0_776:
	s_add_u32 s26, s22, 0xfffc0080
	s_addc_u32 s27, s23, -1
	s_add_i32 s36, 0, 0x10000
	s_cmp_eq_u32 s55, 12
	s_cselect_b32 s31, s15, s27
	s_cselect_b32 s30, s51, s26
	s_cselect_b32 s27, s13, s54
	s_cselect_b32 s26, s52, s53
	s_add_i32 s56, 0, 0x14000
	v_add_u32_e32 v140, s36, v204
	v_add_u32_e32 v156, s56, v204
	ds_read_b128 v[128:131], v140
	ds_read_b128 v[132:135], v140 offset:1024
	ds_read_b128 v[136:139], v140 offset:2048
	ds_read_b128 v[140:143], v140 offset:3072
	ds_read_b128 v[144:147], v156
	ds_read_b128 v[148:151], v156 offset:1024
	ds_read_b128 v[152:155], v156 offset:2048
	ds_read_b128 v[156:159], v156 offset:3072
	s_add_i32 m0, s42, 0xc000
	ds_read_b128 v[182:185], v206
	ds_read_b128 v[186:189], v206 offset:1024
	ds_read_b128 v[190:193], v206 offset:2048
	ds_read_b128 v[194:197], v206 offset:3072
	ds_read_b128 v[198:201], v206 offset:4096
	ds_read_b128 v[208:211], v206 offset:5120
	ds_read_b128 v[212:215], v206 offset:6144
	ds_read_b128 v[228:231], v206 offset:7168
	global_load_lds_dwordx4 v166, s[22:23]
	s_add_i32 m0, s42, 0xe000
	s_nop 0
	global_load_lds_dwordx4 v180, s[22:23]
	s_cmp_lg_u32 s55, vcc_lo
	s_cbranch_scc1 .Lrp_776_0
	global_load_dword v251, v[252:253], off
.Lrp_776_0:
	s_waitcnt vmcnt(8)
	s_waitcnt lgkmcnt(0)
	s_barrier
	v_mfma_f32_16x16x32_bf16 v[124:127], v[128:131], v[182:185], v[124:127]
	v_mfma_f32_16x16x32_bf16 v[124:127], v[132:135], v[186:189], v[124:127]
	v_mfma_f32_16x16x32_bf16 v[120:123], v[140:143], v[186:189], v[120:123]
	v_mfma_f32_16x16x32_bf16 v[120:123], v[136:139], v[182:185], v[120:123]
	v_mfma_f32_16x16x32_bf16 v[116:119], v[144:147], v[182:185], v[116:119]
	v_mfma_f32_16x16x32_bf16 v[116:119], v[148:151], v[186:189], v[116:119]
	v_mfma_f32_16x16x32_bf16 v[112:115], v[156:159], v[186:189], v[112:115]
	v_mfma_f32_16x16x32_bf16 v[112:115], v[152:155], v[182:185], v[112:115]
	v_mfma_f32_16x16x32_bf16 v[96:99], v[152:155], v[190:193], v[96:99]
	v_mfma_f32_16x16x32_bf16 v[96:99], v[156:159], v[194:197], v[96:99]
	v_mfma_f32_16x16x32_bf16 v[100:103], v[148:151], v[194:197], v[100:103]
	v_mfma_f32_16x16x32_bf16 v[100:103], v[144:147], v[190:193], v[100:103]
	v_mfma_f32_16x16x32_bf16 v[104:107], v[136:139], v[190:193], v[104:107]
	v_mfma_f32_16x16x32_bf16 v[104:107], v[140:143], v[194:197], v[104:107]
	v_mfma_f32_16x16x32_bf16 v[108:111], v[132:135], v[194:197], v[108:111]
	v_mfma_f32_16x16x32_bf16 v[108:111], v[128:131], v[190:193], v[108:111]
	v_mfma_f32_16x16x32_bf16 v[92:95], v[128:131], v[198:201], v[92:95]
	v_mfma_f32_16x16x32_bf16 v[92:95], v[132:135], v[208:211], v[92:95]
	v_mfma_f32_16x16x32_bf16 v[88:91], v[140:143], v[208:211], v[88:91]
	v_mfma_f32_16x16x32_bf16 v[88:91], v[136:139], v[198:201], v[88:91]
	v_mfma_f32_16x16x32_bf16 v[84:87], v[144:147], v[198:201], v[84:87]
	v_mfma_f32_16x16x32_bf16 v[84:87], v[148:151], v[208:211], v[84:87]
	v_mfma_f32_16x16x32_bf16 v[80:83], v[156:159], v[208:211], v[80:83]
	v_mfma_f32_16x16x32_bf16 v[80:83], v[152:155], v[198:201], v[80:83]
	v_mfma_f32_16x16x32_bf16 v[64:67], v[152:155], v[212:215], v[64:67]
	v_mfma_f32_16x16x32_bf16 v[64:67], v[156:159], v[228:231], v[64:67]
	v_mfma_f32_16x16x32_bf16 v[68:71], v[148:151], v[228:231], v[68:71]
	v_mfma_f32_16x16x32_bf16 v[68:71], v[144:147], v[212:215], v[68:71]
	v_mfma_f32_16x16x32_bf16 v[72:75], v[136:139], v[212:215], v[72:75]
	v_mfma_f32_16x16x32_bf16 v[72:75], v[140:143], v[228:231], v[72:75]
	v_mfma_f32_16x16x32_bf16 v[76:79], v[132:135], v[228:231], v[76:79]
	v_mfma_f32_16x16x32_bf16 v[76:79], v[128:131], v[212:215], v[76:79]
	s_barrier
	s_add_i32 s36, s36, s35
	s_add_u32 s98, s26, s20
	s_addc_u32 s99, s27, s21
	s_mov_b32 m0, s36
	ds_read_b128 v[182:185], v206 offset:16384
	ds_read_b128 v[186:189], v206 offset:17408
	ds_read_b128 v[190:193], v206 offset:18432
	ds_read_b128 v[194:197], v206 offset:19456
	ds_read_b128 v[198:201], v206 offset:20480
	ds_read_b128 v[208:211], v206 offset:21504
	ds_read_b128 v[212:215], v206 offset:22528
	ds_read_b128 v[228:231], v206 offset:23552
	global_load_lds_dwordx4 v168, s[26:27]
	s_add_i32 m0, s36, 0x2000
	s_add_u32 s36, s26, 0x40000
	s_addc_u32 s37, s27, 0
	s_add_i32 s56, s56, s35
	global_load_lds_dwordx4 v160, s[26:27]
	s_mov_b32 m0, s56
	s_nop 0
	global_load_lds_dwordx4 v168, s[36:37]
	s_add_i32 m0, s56, 0x2000
	s_nop 0
	global_load_lds_dwordx4 v160, s[36:37]
	s_add_u32 s100, s30, s20
	s_addc_u32 s101, s31, s21
	s_mov_b32 m0, s42
	s_nop 0
	global_load_lds_dwordx4 v164, s[30:31]
	s_mov_b32 m0, s43
	s_nop 0
	global_load_lds_dwordx4 v162, s[30:31]
	s_cmp_lg_u32 s55, vcc_lo
	s_cbranch_scc1 .Lrp_776_1
	global_load_dword v251, v[252:253], off offset:128
.Lrp_776_1:
	s_waitcnt vmcnt(8)
	s_waitcnt lgkmcnt(0)
	s_barrier
	v_mfma_f32_16x16x32_bf16 v[60:63], v[128:131], v[182:185], v[60:63]
	v_mfma_f32_16x16x32_bf16 v[60:63], v[132:135], v[186:189], v[60:63]
	v_mfma_f32_16x16x32_bf16 v[56:59], v[140:143], v[186:189], v[56:59]
	v_mfma_f32_16x16x32_bf16 v[56:59], v[136:139], v[182:185], v[56:59]
	v_mfma_f32_16x16x32_bf16 v[52:55], v[144:147], v[182:185], v[52:55]
	v_mfma_f32_16x16x32_bf16 v[52:55], v[148:151], v[186:189], v[52:55]
	v_mfma_f32_16x16x32_bf16 v[48:51], v[156:159], v[186:189], v[48:51]
	v_mfma_f32_16x16x32_bf16 v[48:51], v[152:155], v[182:185], v[48:51]
	v_mfma_f32_16x16x32_bf16 v[32:35], v[152:155], v[190:193], v[32:35]
	v_mfma_f32_16x16x32_bf16 v[32:35], v[156:159], v[194:197], v[32:35]
	v_mfma_f32_16x16x32_bf16 v[36:39], v[148:151], v[194:197], v[36:39]
	v_mfma_f32_16x16x32_bf16 v[36:39], v[144:147], v[190:193], v[36:39]
	v_mfma_f32_16x16x32_bf16 v[40:43], v[136:139], v[190:193], v[40:43]
	v_mfma_f32_16x16x32_bf16 v[40:43], v[140:143], v[194:197], v[40:43]
	v_mfma_f32_16x16x32_bf16 v[44:47], v[132:135], v[194:197], v[44:47]
	v_mfma_f32_16x16x32_bf16 v[44:47], v[128:131], v[190:193], v[44:47]
	v_mfma_f32_16x16x32_bf16 v[28:31], v[128:131], v[198:201], v[28:31]
	v_mfma_f32_16x16x32_bf16 v[28:31], v[132:135], v[208:211], v[28:31]
	v_mfma_f32_16x16x32_bf16 v[24:27], v[140:143], v[208:211], v[24:27]
	v_mfma_f32_16x16x32_bf16 v[24:27], v[136:139], v[198:201], v[24:27]
	v_mfma_f32_16x16x32_bf16 v[20:23], v[144:147], v[198:201], v[20:23]
	v_mfma_f32_16x16x32_bf16 v[20:23], v[148:151], v[208:211], v[20:23]
	v_mfma_f32_16x16x32_bf16 v[16:19], v[156:159], v[208:211], v[16:19]
	v_mfma_f32_16x16x32_bf16 v[16:19], v[152:155], v[198:201], v[16:19]
	v_mfma_f32_16x16x32_bf16 v[0:3], v[152:155], v[212:215], v[0:3]
	v_mfma_f32_16x16x32_bf16 v[0:3], v[156:159], v[228:231], v[0:3]
	v_mfma_f32_16x16x32_bf16 v[4:7], v[148:151], v[228:231], v[4:7]
	v_mfma_f32_16x16x32_bf16 v[4:7], v[144:147], v[212:215], v[4:7]
	v_mfma_f32_16x16x32_bf16 v[8:11], v[136:139], v[212:215], v[8:11]
	v_mfma_f32_16x16x32_bf16 v[8:11], v[140:143], v[228:231], v[8:11]
	v_mfma_f32_16x16x32_bf16 v[12:15], v[132:135], v[228:231], v[12:15]
	v_mfma_f32_16x16x32_bf16 v[12:15], v[128:131], v[212:215], v[12:15]
	s_barrier
	s_add_i32 s36, 0, 0x18000
	s_add_i32 s37, 0, 0x1c000
	v_add_u32_e32 v140, s36, v204
	v_add_u32_e32 v156, s37, v204
	ds_read_b128 v[128:131], v140
	ds_read_b128 v[132:135], v140 offset:1024
	ds_read_b128 v[136:139], v140 offset:2048
	ds_read_b128 v[140:143], v140 offset:3072
	ds_read_b128 v[144:147], v156
	ds_read_b128 v[148:151], v156 offset:1024
	ds_read_b128 v[152:155], v156 offset:2048
	ds_read_b128 v[156:159], v156 offset:3072
	s_add_u32 s30, s30, 0x40000
	s_addc_u32 s31, s31, 0
	s_mov_b32 m0, s44
	ds_read_b128 v[182:185], v206 offset:32768
	ds_read_b128 v[186:189], v206 offset:33792
	ds_read_b128 v[190:193], v206 offset:34816
	ds_read_b128 v[194:197], v206 offset:35840
	ds_read_b128 v[198:201], v206 offset:36864
	ds_read_b128 v[208:211], v206 offset:37888
	ds_read_b128 v[212:215], v206 offset:38912
	ds_read_b128 v[228:231], v206 offset:39936
	global_load_lds_dwordx4 v164, s[30:31]
	s_mov_b32 m0, s45
	s_nop 0
	global_load_lds_dwordx4 v162, s[30:31]
	s_cmp_lg_u32 s55, vcc_lo
	s_cbranch_scc1 .Lrp_776_2
	global_load_dword v251, v[254:255], off
.Lrp_776_2:
	s_waitcnt vmcnt(8)
	s_waitcnt lgkmcnt(0)
	s_barrier
	v_mfma_f32_16x16x32_bf16 v[124:127], v[128:131], v[182:185], v[124:127]
	v_mfma_f32_16x16x32_bf16 v[124:127], v[132:135], v[186:189], v[124:127]
	v_mfma_f32_16x16x32_bf16 v[120:123], v[140:143], v[186:189], v[120:123]
	v_mfma_f32_16x16x32_bf16 v[120:123], v[136:139], v[182:185], v[120:123]
	v_mfma_f32_16x16x32_bf16 v[116:119], v[144:147], v[182:185], v[116:119]
	v_mfma_f32_16x16x32_bf16 v[116:119], v[148:151], v[186:189], v[116:119]
	v_mfma_f32_16x16x32_bf16 v[112:115], v[156:159], v[186:189], v[112:115]
	v_mfma_f32_16x16x32_bf16 v[112:115], v[152:155], v[182:185], v[112:115]
	v_mfma_f32_16x16x32_bf16 v[96:99], v[152:155], v[190:193], v[96:99]
	v_mfma_f32_16x16x32_bf16 v[96:99], v[156:159], v[194:197], v[96:99]
	v_mfma_f32_16x16x32_bf16 v[100:103], v[148:151], v[194:197], v[100:103]
	v_mfma_f32_16x16x32_bf16 v[100:103], v[144:147], v[190:193], v[100:103]
	v_mfma_f32_16x16x32_bf16 v[104:107], v[136:139], v[190:193], v[104:107]
	v_mfma_f32_16x16x32_bf16 v[104:107], v[140:143], v[194:197], v[104:107]
	v_mfma_f32_16x16x32_bf16 v[108:111], v[132:135], v[194:197], v[108:111]
	v_mfma_f32_16x16x32_bf16 v[108:111], v[128:131], v[190:193], v[108:111]
	v_mfma_f32_16x16x32_bf16 v[92:95], v[128:131], v[198:201], v[92:95]
	v_mfma_f32_16x16x32_bf16 v[92:95], v[132:135], v[208:211], v[92:95]
	v_mfma_f32_16x16x32_bf16 v[88:91], v[140:143], v[208:211], v[88:91]
	v_mfma_f32_16x16x32_bf16 v[88:91], v[136:139], v[198:201], v[88:91]
	v_mfma_f32_16x16x32_bf16 v[84:87], v[144:147], v[198:201], v[84:87]
	v_mfma_f32_16x16x32_bf16 v[84:87], v[148:151], v[208:211], v[84:87]
	v_mfma_f32_16x16x32_bf16 v[80:83], v[156:159], v[208:211], v[80:83]
	v_mfma_f32_16x16x32_bf16 v[80:83], v[152:155], v[198:201], v[80:83]
	v_mfma_f32_16x16x32_bf16 v[64:67], v[152:155], v[212:215], v[64:67]
	v_mfma_f32_16x16x32_bf16 v[64:67], v[156:159], v[228:231], v[64:67]
	v_mfma_f32_16x16x32_bf16 v[68:71], v[148:151], v[228:231], v[68:71]
	v_mfma_f32_16x16x32_bf16 v[68:71], v[144:147], v[212:215], v[68:71]
	v_mfma_f32_16x16x32_bf16 v[72:75], v[136:139], v[212:215], v[72:75]
	v_mfma_f32_16x16x32_bf16 v[72:75], v[140:143], v[228:231], v[72:75]
	v_mfma_f32_16x16x32_bf16 v[76:79], v[132:135], v[228:231], v[76:79]
	v_mfma_f32_16x16x32_bf16 v[76:79], v[128:131], v[212:215], v[76:79]
	s_barrier
	s_add_i32 s30, s36, s35
	s_mov_b32 m0, s30
	ds_read_b128 v[182:185], v206 offset:49152
	ds_read_b128 v[186:189], v206 offset:50176
	ds_read_b128 v[190:193], v206 offset:51200
	ds_read_b128 v[194:197], v206 offset:52224
	ds_read_b128 v[198:201], v206 offset:53248
	ds_read_b128 v[208:211], v206 offset:54272
	ds_read_b128 v[212:215], v206 offset:55296
	ds_read_b128 v[228:231], v206 offset:56320
	global_load_lds_dwordx4 v168, s[98:99]
	s_add_i32 m0, s30, 0x2000
	s_add_u32 s26, s26, 0x40080
	s_addc_u32 s27, s27, 0
	s_add_i32 s30, s37, s35
	global_load_lds_dwordx4 v160, s[98:99]
	s_mov_b32 m0, s30
	s_nop 0
	global_load_lds_dwordx4 v168, s[26:27]
	s_add_i32 m0, s30, 0x2000
	s_nop 0
	global_load_lds_dwordx4 v160, s[26:27]
	s_mov_b32 m0, s47
	s_nop 0
	global_load_lds_dwordx4 v164, s[100:101]
	s_mov_b32 m0, s48
	s_nop 0
	global_load_lds_dwordx4 v162, s[100:101]
	s_cmp_lg_u32 s55, vcc_lo
	s_cbranch_scc1 .Lrp_776_3
	global_load_dword v251, v[254:255], off offset:128
.Lrp_776_3:
	s_waitcnt vmcnt(8)
	s_waitcnt lgkmcnt(0)
	s_barrier
	v_mfma_f32_16x16x32_bf16 v[60:63], v[128:131], v[182:185], v[60:63]
	v_mfma_f32_16x16x32_bf16 v[60:63], v[132:135], v[186:189], v[60:63]
	v_mfma_f32_16x16x32_bf16 v[56:59], v[140:143], v[186:189], v[56:59]
	v_mfma_f32_16x16x32_bf16 v[56:59], v[136:139], v[182:185], v[56:59]
	v_mfma_f32_16x16x32_bf16 v[52:55], v[144:147], v[182:185], v[52:55]
	v_mfma_f32_16x16x32_bf16 v[52:55], v[148:151], v[186:189], v[52:55]
	v_mfma_f32_16x16x32_bf16 v[48:51], v[156:159], v[186:189], v[48:51]
	v_mfma_f32_16x16x32_bf16 v[48:51], v[152:155], v[182:185], v[48:51]
	v_mfma_f32_16x16x32_bf16 v[32:35], v[152:155], v[190:193], v[32:35]
	v_mfma_f32_16x16x32_bf16 v[32:35], v[156:159], v[194:197], v[32:35]
	v_mfma_f32_16x16x32_bf16 v[36:39], v[148:151], v[194:197], v[36:39]
	v_mfma_f32_16x16x32_bf16 v[36:39], v[144:147], v[190:193], v[36:39]
	v_mfma_f32_16x16x32_bf16 v[40:43], v[136:139], v[190:193], v[40:43]
	v_mfma_f32_16x16x32_bf16 v[40:43], v[140:143], v[194:197], v[40:43]
	v_mfma_f32_16x16x32_bf16 v[44:47], v[132:135], v[194:197], v[44:47]
	v_mfma_f32_16x16x32_bf16 v[44:47], v[128:131], v[190:193], v[44:47]
	v_mfma_f32_16x16x32_bf16 v[28:31], v[128:131], v[198:201], v[28:31]
	v_mfma_f32_16x16x32_bf16 v[28:31], v[132:135], v[208:211], v[28:31]
	v_mfma_f32_16x16x32_bf16 v[24:27], v[140:143], v[208:211], v[24:27]
	v_mfma_f32_16x16x32_bf16 v[24:27], v[136:139], v[198:201], v[24:27]
	v_mfma_f32_16x16x32_bf16 v[20:23], v[144:147], v[198:201], v[20:23]
	v_mfma_f32_16x16x32_bf16 v[20:23], v[148:151], v[208:211], v[20:23]
	v_mfma_f32_16x16x32_bf16 v[16:19], v[156:159], v[208:211], v[16:19]
	v_mfma_f32_16x16x32_bf16 v[16:19], v[152:155], v[198:201], v[16:19]
	v_mfma_f32_16x16x32_bf16 v[0:3], v[152:155], v[212:215], v[0:3]
	v_mfma_f32_16x16x32_bf16 v[0:3], v[156:159], v[228:231], v[0:3]
	v_mfma_f32_16x16x32_bf16 v[4:7], v[148:151], v[228:231], v[4:7]
	v_mfma_f32_16x16x32_bf16 v[4:7], v[144:147], v[212:215], v[4:7]
	v_mfma_f32_16x16x32_bf16 v[8:11], v[136:139], v[212:215], v[8:11]
	v_mfma_f32_16x16x32_bf16 v[8:11], v[140:143], v[228:231], v[8:11]
	v_mfma_f32_16x16x32_bf16 v[12:15], v[132:135], v[228:231], v[12:15]
	v_mfma_f32_16x16x32_bf16 v[12:15], v[128:131], v[212:215], v[12:15]
	s_barrier
	s_add_i32 s55, s55, 2
	s_add_u32 s22, s22, 0x100
	s_addc_u32 s23, s23, 0
	s_add_u32 s53, s53, 0x100
	s_addc_u32 s54, s54, 0
	s_cmp_gt_u32 s55, 13
	s_cbranch_scc0 .LBB0_776
	s_and_b64 vcc, exec, s[10:11]
	s_cbranch_vccz .LBB0_779
	s_barrier

.LBB0_985:
	s_ashr_i32 s23, s22, 31
	s_lshl_b64 s[26:27], s[22:23], 21
	v_readlane_b32 s30, v250, 6
	v_readlane_b32 s31, v250, 7
	s_add_u32 s26, s30, s26
	s_addc_u32 s27, s31, s27
	s_and_b64 s[30:31], s[6:7], exec
	s_cselect_b32 s23, s27, s9
	s_cselect_b32 s53, s26, s8
	s_ashr_i32 s19, s18, 31
	s_lshl_b64 s[30:31], s[18:19], 21
	s_add_u32 s30, s5, s30
	s_addc_u32 s31, s42, s31
	s_and_b64 s[36:37], s[6:7], exec
	s_cselect_b32 s19, s31, s35
	s_cselect_b32 s54, s30, s34
	s_add_u32 s8, s8, 0x100080
	s_addc_u32 s9, s9, 0
	s_add_u32 s55, s34, 0x100
	v_mov_b32_e32 v0, 0
	s_addc_u32 s56, s35, 0
	s_mov_b32 s57, -2
	s_waitcnt lgkmcnt(0)
	v_mov_b32_e32 v1, v0
	v_mov_b32_e32 v2, v0
	v_mov_b32_e32 v3, v0
	v_mov_b32_e32 v4, v0
	v_mov_b32_e32 v5, v0
	v_mov_b32_e32 v6, v0
	v_mov_b32_e32 v7, v0
	v_mov_b32_e32 v16, v0
	v_mov_b32_e32 v17, v0
	v_mov_b32_e32 v18, v0
	v_mov_b32_e32 v19, v0
	v_mov_b32_e32 v20, v0
	v_mov_b32_e32 v21, v0
	v_mov_b32_e32 v22, v0
	v_mov_b32_e32 v23, v0
	v_mov_b32_e32 v32, v0
	v_mov_b32_e32 v33, v0
	v_mov_b32_e32 v34, v0
	v_mov_b32_e32 v35, v0
	v_mov_b32_e32 v36, v0
	v_mov_b32_e32 v37, v0
	v_mov_b32_e32 v38, v0
	v_mov_b32_e32 v39, v0
	v_mov_b32_e32 v48, v0
	v_mov_b32_e32 v49, v0
	v_mov_b32_e32 v50, v0
	v_mov_b32_e32 v51, v0
	v_mov_b32_e32 v52, v0
	v_mov_b32_e32 v53, v0
	v_mov_b32_e32 v54, v0
	v_mov_b32_e32 v55, v0
	v_mov_b32_e32 v8, v0
	v_mov_b32_e32 v9, v0
	v_mov_b32_e32 v10, v0
	v_mov_b32_e32 v11, v0
	v_mov_b32_e32 v12, v0
	v_mov_b32_e32 v13, v0
	v_mov_b32_e32 v14, v0
	v_mov_b32_e32 v15, v0
	v_mov_b32_e32 v24, v0
	v_mov_b32_e32 v25, v0
	v_mov_b32_e32 v26, v0
	v_mov_b32_e32 v27, v0
	v_mov_b32_e32 v28, v0
	v_mov_b32_e32 v29, v0
	v_mov_b32_e32 v30, v0
	v_mov_b32_e32 v31, v0
	v_mov_b32_e32 v40, v0
	v_mov_b32_e32 v41, v0
	v_mov_b32_e32 v42, v0
	v_mov_b32_e32 v43, v0
	v_mov_b32_e32 v44, v0
	v_mov_b32_e32 v45, v0
	v_mov_b32_e32 v46, v0
	v_mov_b32_e32 v47, v0
	v_mov_b32_e32 v56, v0
	v_mov_b32_e32 v57, v0
	v_mov_b32_e32 v58, v0
	v_mov_b32_e32 v59, v0
	v_mov_b32_e32 v60, v0
	v_mov_b32_e32 v61, v0
	v_mov_b32_e32 v62, v0
	v_mov_b32_e32 v63, v0
	v_mov_b32_e32 v64, v0
	v_mov_b32_e32 v65, v0
	v_mov_b32_e32 v66, v0
	v_mov_b32_e32 v67, v0
	v_mov_b32_e32 v68, v0
	v_mov_b32_e32 v69, v0
	v_mov_b32_e32 v70, v0
	v_mov_b32_e32 v71, v0
	v_mov_b32_e32 v80, v0
	v_mov_b32_e32 v81, v0
	v_mov_b32_e32 v82, v0
	v_mov_b32_e32 v83, v0
	v_mov_b32_e32 v84, v0
	v_mov_b32_e32 v85, v0
	v_mov_b32_e32 v86, v0
	v_mov_b32_e32 v87, v0
	v_mov_b32_e32 v96, v0
	v_mov_b32_e32 v97, v0
	v_mov_b32_e32 v98, v0
	v_mov_b32_e32 v99, v0
	v_mov_b32_e32 v100, v0
	v_mov_b32_e32 v101, v0
	v_mov_b32_e32 v102, v0
	v_mov_b32_e32 v103, v0
	v_mov_b32_e32 v112, v0
	v_mov_b32_e32 v113, v0
	v_mov_b32_e32 v114, v0
	v_mov_b32_e32 v115, v0
	v_mov_b32_e32 v116, v0
	v_mov_b32_e32 v117, v0
	v_mov_b32_e32 v118, v0
	v_mov_b32_e32 v119, v0
	v_mov_b32_e32 v72, v0
	v_mov_b32_e32 v73, v0
	v_mov_b32_e32 v74, v0
	v_mov_b32_e32 v75, v0
	v_mov_b32_e32 v76, v0
	v_mov_b32_e32 v77, v0
	v_mov_b32_e32 v78, v0
	v_mov_b32_e32 v79, v0
	v_mov_b32_e32 v88, v0
	v_mov_b32_e32 v89, v0
	v_mov_b32_e32 v90, v0
	v_mov_b32_e32 v91, v0
	v_mov_b32_e32 v92, v0
	v_mov_b32_e32 v93, v0
	v_mov_b32_e32 v94, v0
	v_mov_b32_e32 v95, v0
	v_mov_b32_e32 v104, v0
	v_mov_b32_e32 v105, v0
	v_mov_b32_e32 v106, v0
	v_mov_b32_e32 v107, v0
	v_mov_b32_e32 v108, v0
	v_mov_b32_e32 v109, v0
	v_mov_b32_e32 v110, v0
	v_mov_b32_e32 v111, v0
	v_mov_b32_e32 v120, v0
	v_mov_b32_e32 v121, v0
	v_mov_b32_e32 v122, v0
	v_mov_b32_e32 v123, v0
	v_mov_b32_e32 v124, v0
	v_mov_b32_e32 v125, v0
	v_mov_b32_e32 v126, v0
	v_mov_b32_e32 v127, v0
	v_lshrrev_b32_e32 v251, 1, v216
	v_lshl_add_u32 v251, s24, 8, v251
	v_lshlrev_b32_e32 v251, 11, v251
	v_and_b32_e32 v254, 1, v216
	v_lshl_add_u32 v251, v254, 8, v251
	v_lshl_add_u32 v254, s52, 9, v251
	v_mov_b32_e32 v255, 0
	v_readlane_b32 vcc_lo, v247, 5
	v_readlane_b32 vcc_hi, v247, 6
	s_nop 1
	v_lshl_add_u64 v[252:253], vcc, 0, v[254:255]
	v_readlane_b32 vcc_lo, v249, 0
	v_readlane_b32 vcc_hi, v249, 1
	s_nop 1
	v_lshl_add_u64 v[254:255], vcc, 0, v[254:255]
	v_readfirstlane_b32 vcc_lo, v216
	s_nop 3
	s_lshr_b32 vcc_lo, vcc_lo, 6
	s_lshl_b32 vcc_lo, vcc_lo, 3
.LBB0_986:
	s_add_u32 s34, s8, 0xfff00080
	s_addc_u32 s35, s9, -1
	s_add_i32 s36, 0, 0x10000
	s_cmp_eq_u32 s57, 60
	s_cselect_b32 s41, s23, s35
	s_cselect_b32 s40, s53, s34
	s_cselect_b32 s35, s19, s56
	s_cselect_b32 s34, s54, s55
	s_add_i32 s58, 0, 0x14000
	v_add_u32_e32 v140, s36, v228
	v_add_u32_e32 v156, s58, v228
	ds_read_b128 v[128:131], v140
	ds_read_b128 v[132:135], v140 offset:1024
	ds_read_b128 v[136:139], v140 offset:2048
	ds_read_b128 v[140:143], v140 offset:3072
	ds_read_b128 v[144:147], v156
	ds_read_b128 v[148:151], v156 offset:1024
	ds_read_b128 v[152:155], v156 offset:2048
	ds_read_b128 v[156:159], v156 offset:3072
	s_add_i32 m0, s44, 0xc000
	ds_read_b128 v[160:163], v230
	ds_read_b128 v[164:167], v230 offset:1024
	ds_read_b128 v[190:193], v230 offset:2048
	ds_read_b128 v[194:197], v230 offset:3072
	ds_read_b128 v[198:201], v230 offset:4096
	ds_read_b128 v[202:205], v230 offset:5120
	ds_read_b128 v[206:209], v230 offset:6144
	ds_read_b128 v[210:213], v230 offset:7168
	global_load_lds_dwordx4 v186, s[8:9]
	s_add_i32 m0, s44, 0xe000
	s_nop 0
	global_load_lds_dwordx4 v188, s[8:9]
	s_cmp_lg_u32 s57, vcc_lo
	s_cbranch_scc1 .Lrp_986_0
	global_load_dword v251, v[252:253], off
.Lrp_986_0:
	s_waitcnt vmcnt(8)
	s_waitcnt lgkmcnt(0)
	s_barrier
	v_mfma_f32_16x16x32_bf16 v[124:127], v[128:131], v[160:163], v[124:127]
	v_mfma_f32_16x16x32_bf16 v[124:127], v[132:135], v[164:167], v[124:127]
	v_mfma_f32_16x16x32_bf16 v[120:123], v[140:143], v[164:167], v[120:123]
	v_mfma_f32_16x16x32_bf16 v[120:123], v[136:139], v[160:163], v[120:123]
	v_mfma_f32_16x16x32_bf16 v[116:119], v[144:147], v[160:163], v[116:119]
	v_mfma_f32_16x16x32_bf16 v[116:119], v[148:151], v[164:167], v[116:119]
	v_mfma_f32_16x16x32_bf16 v[112:115], v[156:159], v[164:167], v[112:115]
	v_mfma_f32_16x16x32_bf16 v[112:115], v[152:155], v[160:163], v[112:115]
	v_mfma_f32_16x16x32_bf16 v[96:99], v[152:155], v[190:193], v[96:99]
	v_mfma_f32_16x16x32_bf16 v[96:99], v[156:159], v[194:197], v[96:99]
	v_mfma_f32_16x16x32_bf16 v[100:103], v[148:151], v[194:197], v[100:103]
	v_mfma_f32_16x16x32_bf16 v[100:103], v[144:147], v[190:193], v[100:103]
	v_mfma_f32_16x16x32_bf16 v[104:107], v[136:139], v[190:193], v[104:107]
	v_mfma_f32_16x16x32_bf16 v[104:107], v[140:143], v[194:197], v[104:107]
	v_mfma_f32_16x16x32_bf16 v[108:111], v[132:135], v[194:197], v[108:111]
	v_mfma_f32_16x16x32_bf16 v[108:111], v[128:131], v[190:193], v[108:111]
	v_mfma_f32_16x16x32_bf16 v[92:95], v[128:131], v[198:201], v[92:95]
	v_mfma_f32_16x16x32_bf16 v[92:95], v[132:135], v[202:205], v[92:95]
	v_mfma_f32_16x16x32_bf16 v[88:91], v[140:143], v[202:205], v[88:91]
	v_mfma_f32_16x16x32_bf16 v[88:91], v[136:139], v[198:201], v[88:91]
	v_mfma_f32_16x16x32_bf16 v[84:87], v[144:147], v[198:201], v[84:87]
	v_mfma_f32_16x16x32_bf16 v[84:87], v[148:151], v[202:205], v[84:87]
	v_mfma_f32_16x16x32_bf16 v[80:83], v[156:159], v[202:205], v[80:83]
	v_mfma_f32_16x16x32_bf16 v[80:83], v[152:155], v[198:201], v[80:83]
	v_mfma_f32_16x16x32_bf16 v[64:67], v[152:155], v[206:209], v[64:67]
	v_mfma_f32_16x16x32_bf16 v[64:67], v[156:159], v[210:213], v[64:67]
	v_mfma_f32_16x16x32_bf16 v[68:71], v[148:151], v[210:213], v[68:71]
	v_mfma_f32_16x16x32_bf16 v[68:71], v[144:147], v[206:209], v[68:71]
	v_mfma_f32_16x16x32_bf16 v[72:75], v[136:139], v[206:209], v[72:75]
	v_mfma_f32_16x16x32_bf16 v[72:75], v[140:143], v[210:213], v[72:75]
	v_mfma_f32_16x16x32_bf16 v[76:79], v[132:135], v[210:213], v[76:79]
	v_mfma_f32_16x16x32_bf16 v[76:79], v[128:131], v[206:209], v[76:79]
	s_barrier
	s_add_i32 s36, s36, s43
	s_add_u32 s98, s34, s20
	s_addc_u32 s99, s35, s21
	s_mov_b32 m0, s36
	ds_read_b128 v[160:163], v230 offset:16384
	ds_read_b128 v[164:167], v230 offset:17408
	ds_read_b128 v[190:193], v230 offset:18432
	ds_read_b128 v[194:197], v230 offset:19456
	ds_read_b128 v[198:201], v230 offset:20480
	ds_read_b128 v[202:205], v230 offset:21504
	ds_read_b128 v[206:209], v230 offset:22528
	ds_read_b128 v[210:213], v230 offset:23552
	global_load_lds_dwordx4 v168, s[34:35]
	s_add_i32 m0, s36, 0x2000
	s_add_u32 s36, s34, 0x100000
	s_addc_u32 s37, s35, 0
	s_add_i32 s58, s58, s43
	global_load_lds_dwordx4 v180, s[34:35]
	s_mov_b32 m0, s58
	s_nop 0
	global_load_lds_dwordx4 v168, s[36:37]
	s_add_i32 m0, s58, 0x2000
	s_nop 0
	global_load_lds_dwordx4 v180, s[36:37]
	s_add_u32 s100, s40, s20
	s_addc_u32 s101, s41, s21
	s_mov_b32 m0, s44
	s_nop 0
	global_load_lds_dwordx4 v184, s[40:41]
	s_mov_b32 m0, s45
	s_nop 0
	global_load_lds_dwordx4 v182, s[40:41]
	s_cmp_lg_u32 s57, vcc_lo
	s_cbranch_scc1 .Lrp_986_1
	global_load_dword v251, v[252:253], off offset:128
.Lrp_986_1:
	s_waitcnt vmcnt(8)
	s_waitcnt lgkmcnt(0)
	s_barrier
	v_mfma_f32_16x16x32_bf16 v[60:63], v[128:131], v[160:163], v[60:63]
	v_mfma_f32_16x16x32_bf16 v[60:63], v[132:135], v[164:167], v[60:63]
	v_mfma_f32_16x16x32_bf16 v[56:59], v[140:143], v[164:167], v[56:59]
	v_mfma_f32_16x16x32_bf16 v[56:59], v[136:139], v[160:163], v[56:59]
	v_mfma_f32_16x16x32_bf16 v[52:55], v[144:147], v[160:163], v[52:55]
	v_mfma_f32_16x16x32_bf16 v[52:55], v[148:151], v[164:167], v[52:55]
	v_mfma_f32_16x16x32_bf16 v[48:51], v[156:159], v[164:167], v[48:51]
	v_mfma_f32_16x16x32_bf16 v[48:51], v[152:155], v[160:163], v[48:51]
	v_mfma_f32_16x16x32_bf16 v[32:35], v[152:155], v[190:193], v[32:35]
	v_mfma_f32_16x16x32_bf16 v[32:35], v[156:159], v[194:197], v[32:35]
	v_mfma_f32_16x16x32_bf16 v[36:39], v[148:151], v[194:197], v[36:39]
	v_mfma_f32_16x16x32_bf16 v[36:39], v[144:147], v[190:193], v[36:39]
	v_mfma_f32_16x16x32_bf16 v[40:43], v[136:139], v[190:193], v[40:43]
	v_mfma_f32_16x16x32_bf16 v[40:43], v[140:143], v[194:197], v[40:43]
	v_mfma_f32_16x16x32_bf16 v[44:47], v[132:135], v[194:197], v[44:47]
	v_mfma_f32_16x16x32_bf16 v[44:47], v[128:131], v[190:193], v[44:47]
	v_mfma_f32_16x16x32_bf16 v[28:31], v[128:131], v[198:201], v[28:31]
	v_mfma_f32_16x16x32_bf16 v[28:31], v[132:135], v[202:205], v[28:31]
	v_mfma_f32_16x16x32_bf16 v[24:27], v[140:143], v[202:205], v[24:27]
	v_mfma_f32_16x16x32_bf16 v[24:27], v[136:139], v[198:201], v[24:27]
	v_mfma_f32_16x16x32_bf16 v[20:23], v[144:147], v[198:201], v[20:23]
	v_mfma_f32_16x16x32_bf16 v[20:23], v[148:151], v[202:205], v[20:23]
	v_mfma_f32_16x16x32_bf16 v[16:19], v[156:159], v[202:205], v[16:19]
	v_mfma_f32_16x16x32_bf16 v[16:19], v[152:155], v[198:201], v[16:19]
	v_mfma_f32_16x16x32_bf16 v[0:3], v[152:155], v[206:209], v[0:3]
	v_mfma_f32_16x16x32_bf16 v[0:3], v[156:159], v[210:213], v[0:3]
	v_mfma_f32_16x16x32_bf16 v[4:7], v[148:151], v[210:213], v[4:7]
	v_mfma_f32_16x16x32_bf16 v[4:7], v[144:147], v[206:209], v[4:7]
	v_mfma_f32_16x16x32_bf16 v[8:11], v[136:139], v[206:209], v[8:11]
	v_mfma_f32_16x16x32_bf16 v[8:11], v[140:143], v[210:213], v[8:11]
	v_mfma_f32_16x16x32_bf16 v[12:15], v[132:135], v[210:213], v[12:15]
	v_mfma_f32_16x16x32_bf16 v[12:15], v[128:131], v[206:209], v[12:15]
	s_barrier
	s_add_i32 s58, 0, 0x18000
	s_add_i32 s59, 0, 0x1c000
	v_add_u32_e32 v140, s58, v228
	v_add_u32_e32 v156, s59, v228
	ds_read_b128 v[128:131], v140
	ds_read_b128 v[132:135], v140 offset:1024
	ds_read_b128 v[136:139], v140 offset:2048
	ds_read_b128 v[140:143], v140 offset:3072
	ds_read_b128 v[144:147], v156
	ds_read_b128 v[148:151], v156 offset:1024
	ds_read_b128 v[152:155], v156 offset:2048
	ds_read_b128 v[156:159], v156 offset:3072
	s_add_u32 s36, s40, 0x100000
	s_addc_u32 s37, s41, 0
	s_mov_b32 m0, s46
	ds_read_b128 v[160:163], v230 offset:32768
	ds_read_b128 v[164:167], v230 offset:33792
	ds_read_b128 v[190:193], v230 offset:34816
	ds_read_b128 v[194:197], v230 offset:35840
	ds_read_b128 v[198:201], v230 offset:36864
	ds_read_b128 v[202:205], v230 offset:37888
	ds_read_b128 v[206:209], v230 offset:38912
	ds_read_b128 v[210:213], v230 offset:39936
	global_load_lds_dwordx4 v184, s[36:37]
	s_mov_b32 m0, s47
	s_nop 0
	global_load_lds_dwordx4 v182, s[36:37]
	s_cmp_lg_u32 s57, vcc_lo
	s_cbranch_scc1 .Lrp_986_2
	global_load_dword v251, v[254:255], off
.Lrp_986_2:
	s_waitcnt vmcnt(8)
	s_waitcnt lgkmcnt(0)
	s_barrier
	v_mfma_f32_16x16x32_bf16 v[124:127], v[128:131], v[160:163], v[124:127]
	v_mfma_f32_16x16x32_bf16 v[124:127], v[132:135], v[164:167], v[124:127]
	v_mfma_f32_16x16x32_bf16 v[120:123], v[140:143], v[164:167], v[120:123]
	v_mfma_f32_16x16x32_bf16 v[120:123], v[136:139], v[160:163], v[120:123]
	v_mfma_f32_16x16x32_bf16 v[116:119], v[144:147], v[160:163], v[116:119]
	v_mfma_f32_16x16x32_bf16 v[116:119], v[148:151], v[164:167], v[116:119]
	v_mfma_f32_16x16x32_bf16 v[112:115], v[156:159], v[164:167], v[112:115]
	v_mfma_f32_16x16x32_bf16 v[112:115], v[152:155], v[160:163], v[112:115]
	v_mfma_f32_16x16x32_bf16 v[96:99], v[152:155], v[190:193], v[96:99]
	v_mfma_f32_16x16x32_bf16 v[96:99], v[156:159], v[194:197], v[96:99]
	v_mfma_f32_16x16x32_bf16 v[100:103], v[148:151], v[194:197], v[100:103]
	v_mfma_f32_16x16x32_bf16 v[100:103], v[144:147], v[190:193], v[100:103]
	v_mfma_f32_16x16x32_bf16 v[104:107], v[136:139], v[190:193], v[104:107]
	v_mfma_f32_16x16x32_bf16 v[104:107], v[140:143], v[194:197], v[104:107]
	v_mfma_f32_16x16x32_bf16 v[108:111], v[132:135], v[194:197], v[108:111]
	v_mfma_f32_16x16x32_bf16 v[108:111], v[128:131], v[190:193], v[108:111]
	v_mfma_f32_16x16x32_bf16 v[92:95], v[128:131], v[198:201], v[92:95]
	v_mfma_f32_16x16x32_bf16 v[92:95], v[132:135], v[202:205], v[92:95]
	v_mfma_f32_16x16x32_bf16 v[88:91], v[140:143], v[202:205], v[88:91]
	v_mfma_f32_16x16x32_bf16 v[88:91], v[136:139], v[198:201], v[88:91]
	v_mfma_f32_16x16x32_bf16 v[84:87], v[144:147], v[198:201], v[84:87]
	v_mfma_f32_16x16x32_bf16 v[84:87], v[148:151], v[202:205], v[84:87]
	v_mfma_f32_16x16x32_bf16 v[80:83], v[156:159], v[202:205], v[80:83]
	v_mfma_f32_16x16x32_bf16 v[80:83], v[152:155], v[198:201], v[80:83]
	v_mfma_f32_16x16x32_bf16 v[64:67], v[152:155], v[206:209], v[64:67]
	v_mfma_f32_16x16x32_bf16 v[64:67], v[156:159], v[210:213], v[64:67]
	v_mfma_f32_16x16x32_bf16 v[68:71], v[148:151], v[210:213], v[68:71]
	v_mfma_f32_16x16x32_bf16 v[68:71], v[144:147], v[206:209], v[68:71]
	v_mfma_f32_16x16x32_bf16 v[72:75], v[136:139], v[206:209], v[72:75]
	v_mfma_f32_16x16x32_bf16 v[72:75], v[140:143], v[210:213], v[72:75]
	v_mfma_f32_16x16x32_bf16 v[76:79], v[132:135], v[210:213], v[76:79]
	v_mfma_f32_16x16x32_bf16 v[76:79], v[128:131], v[206:209], v[76:79]
	s_barrier
	s_add_i32 s36, s58, s43
	s_mov_b32 m0, s36
	ds_read_b128 v[160:163], v230 offset:49152
	ds_read_b128 v[164:167], v230 offset:50176
	ds_read_b128 v[190:193], v230 offset:51200
	ds_read_b128 v[194:197], v230 offset:52224
	ds_read_b128 v[198:201], v230 offset:53248
	ds_read_b128 v[202:205], v230 offset:54272
	ds_read_b128 v[206:209], v230 offset:55296
	ds_read_b128 v[210:213], v230 offset:56320
	global_load_lds_dwordx4 v168, s[98:99]
	s_add_i32 m0, s36, 0x2000
	s_add_u32 s34, s34, 0x100080
	s_addc_u32 s35, s35, 0
	s_add_i32 s36, s59, s43
	global_load_lds_dwordx4 v180, s[98:99]
	s_mov_b32 m0, s36
	s_nop 0
	global_load_lds_dwordx4 v168, s[34:35]
	s_add_i32 m0, s36, 0x2000
	s_nop 0
	global_load_lds_dwordx4 v180, s[34:35]
	s_mov_b32 m0, s50
	s_nop 0
	global_load_lds_dwordx4 v184, s[100:101]
	s_mov_b32 m0, s51
	s_nop 0
	global_load_lds_dwordx4 v182, s[100:101]
	s_cmp_lg_u32 s57, vcc_lo
	s_cbranch_scc1 .Lrp_986_3
	global_load_dword v251, v[254:255], off offset:128
.Lrp_986_3:
	s_waitcnt vmcnt(8)
	s_waitcnt lgkmcnt(0)
	s_barrier
	v_mfma_f32_16x16x32_bf16 v[60:63], v[128:131], v[160:163], v[60:63]
	v_mfma_f32_16x16x32_bf16 v[60:63], v[132:135], v[164:167], v[60:63]
	v_mfma_f32_16x16x32_bf16 v[56:59], v[140:143], v[164:167], v[56:59]
	v_mfma_f32_16x16x32_bf16 v[56:59], v[136:139], v[160:163], v[56:59]
	v_mfma_f32_16x16x32_bf16 v[52:55], v[144:147], v[160:163], v[52:55]
	v_mfma_f32_16x16x32_bf16 v[52:55], v[148:151], v[164:167], v[52:55]
	v_mfma_f32_16x16x32_bf16 v[48:51], v[156:159], v[164:167], v[48:51]
	v_mfma_f32_16x16x32_bf16 v[48:51], v[152:155], v[160:163], v[48:51]
	v_mfma_f32_16x16x32_bf16 v[32:35], v[152:155], v[190:193], v[32:35]
	v_mfma_f32_16x16x32_bf16 v[32:35], v[156:159], v[194:197], v[32:35]
	v_mfma_f32_16x16x32_bf16 v[36:39], v[148:151], v[194:197], v[36:39]
	v_mfma_f32_16x16x32_bf16 v[36:39], v[144:147], v[190:193], v[36:39]
	v_mfma_f32_16x16x32_bf16 v[40:43], v[136:139], v[190:193], v[40:43]
	v_mfma_f32_16x16x32_bf16 v[40:43], v[140:143], v[194:197], v[40:43]
	v_mfma_f32_16x16x32_bf16 v[44:47], v[132:135], v[194:197], v[44:47]
	v_mfma_f32_16x16x32_bf16 v[44:47], v[128:131], v[190:193], v[44:47]
	v_mfma_f32_16x16x32_bf16 v[28:31], v[128:131], v[198:201], v[28:31]
	v_mfma_f32_16x16x32_bf16 v[28:31], v[132:135], v[202:205], v[28:31]
	v_mfma_f32_16x16x32_bf16 v[24:27], v[140:143], v[202:205], v[24:27]
	v_mfma_f32_16x16x32_bf16 v[24:27], v[136:139], v[198:201], v[24:27]
	v_mfma_f32_16x16x32_bf16 v[20:23], v[144:147], v[198:201], v[20:23]
	v_mfma_f32_16x16x32_bf16 v[20:23], v[148:151], v[202:205], v[20:23]
	v_mfma_f32_16x16x32_bf16 v[16:19], v[156:159], v[202:205], v[16:19]
	v_mfma_f32_16x16x32_bf16 v[16:19], v[152:155], v[198:201], v[16:19]
	v_mfma_f32_16x16x32_bf16 v[0:3], v[152:155], v[206:209], v[0:3]
	v_mfma_f32_16x16x32_bf16 v[0:3], v[156:159], v[210:213], v[0:3]
	v_mfma_f32_16x16x32_bf16 v[4:7], v[148:151], v[210:213], v[4:7]
	v_mfma_f32_16x16x32_bf16 v[4:7], v[144:147], v[206:209], v[4:7]
	v_mfma_f32_16x16x32_bf16 v[8:11], v[136:139], v[206:209], v[8:11]
	v_mfma_f32_16x16x32_bf16 v[8:11], v[140:143], v[210:213], v[8:11]
	v_mfma_f32_16x16x32_bf16 v[12:15], v[132:135], v[210:213], v[12:15]
	v_mfma_f32_16x16x32_bf16 v[12:15], v[128:131], v[206:209], v[12:15]
	s_barrier
	s_add_i32 s57, s57, 2
	s_add_u32 s8, s8, 0x100
	s_addc_u32 s9, s9, 0
	s_add_u32 s55, s55, 0x100
	s_addc_u32 s56, s56, 0
	s_cmp_gt_u32 s57, 61
	s_cbranch_scc0 .LBB0_986
	s_and_b64 vcc, exec, s[12:13]
	s_cbranch_vccz .LBB0_989
	s_barrier

	.amdhsa_kernel _Z9trunk_fwd4Args
		.amdhsa_group_segment_fixed_size 0
		.amdhsa_private_segment_fixed_size 0
		.amdhsa_kernarg_size 464
		.amdhsa_user_sgpr_count 2
		.amdhsa_user_sgpr_dispatch_ptr 0
		.amdhsa_user_sgpr_queue_ptr 0
		.amdhsa_user_sgpr_kernarg_segment_ptr 1
		.amdhsa_user_sgpr_dispatch_id 0
		.amdhsa_user_sgpr_kernarg_preload_length 0
		.amdhsa_user_sgpr_kernarg_preload_offset 0
		.amdhsa_user_sgpr_private_segment_size 0
		.amdhsa_uses_dynamic_stack 0
		.amdhsa_enable_private_segment 0
		.amdhsa_system_sgpr_workgroup_id_x 1
		.amdhsa_system_sgpr_workgroup_id_y 0
		.amdhsa_system_sgpr_workgroup_id_z 0
		.amdhsa_system_sgpr_workgroup_info 0
		.amdhsa_system_vgpr_workitem_id 2
		.amdhsa_next_free_vgpr 256
		.amdhsa_next_free_sgpr 102
		.amdhsa_accum_offset 256
		.amdhsa_reserve_vcc 1
		.amdhsa_float_round_mode_32 0
		.amdhsa_float_round_mode_16_64 0
		.amdhsa_float_denorm_mode_32 3
		.amdhsa_float_denorm_mode_16_64 3
		.amdhsa_dx10_clamp 1
		.amdhsa_ieee_mode 1
		.amdhsa_fp16_overflow 0
		.amdhsa_tg_split 0
		.amdhsa_exception_fp_ieee_invalid_op 0
		.amdhsa_exception_fp_denorm_src 0
		.amdhsa_exception_fp_ieee_div_zero 0
		.amdhsa_exception_fp_ieee_overflow 0
		.amdhsa_exception_fp_ieee_underflow 0
		.amdhsa_exception_fp_ieee_inexact 0
		.amdhsa_exception_int_div_zero 0
	.end_amdhsa_kernel

amdhsa.kernels:
  - .agpr_count:     0
    .args:
      - .offset:         0
        .size:           208
        .value_kind:     by_value
      - .offset:         208
        .size:           4
        .value_kind:     hidden_block_count_x
      - .offset:         212
        .size:           4
        .value_kind:     hidden_block_count_y
      - .offset:         216
        .size:           4
        .value_kind:     hidden_block_count_z
      - .offset:         220
        .size:           2
        .value_kind:     hidden_group_size_x
      - .offset:         222
        .size:           2
        .value_kind:     hidden_group_size_y
      - .offset:         224
        .size:           2
        .value_kind:     hidden_group_size_z
      - .offset:         226
        .size:           2
        .value_kind:     hidden_remainder_x
      - .offset:         228
        .size:           2
        .value_kind:     hidden_remainder_y
      - .offset:         230
        .size:           2
        .value_kind:     hidden_remainder_z
      - .offset:         248
        .size:           8
        .value_kind:     hidden_global_offset_x
      - .offset:         256
        .size:           8
        .value_kind:     hidden_global_offset_y
      - .offset:         264
        .size:           8
        .value_kind:     hidden_global_offset_z
      - .offset:         272
        .size:           2
        .value_kind:     hidden_grid_dims
      - .offset:         296
        .size:           8
        .value_kind:     hidden_multigrid_sync_arg
      - .offset:         328
        .size:           4
        .value_kind:     hidden_dynamic_lds_size
    .group_segment_fixed_size: 0
    .kernarg_segment_align: 8
    .kernarg_segment_size: 464
    .language:       OpenCL C
    .language_version:
      - 2
      - 0
    .max_flat_workgroup_size: 512
    .name:           _Z9trunk_fwd4Args
    .private_segment_fixed_size: 0
    .sgpr_count:     108
    .sgpr_spill_count: 324
    .symbol:         _Z9trunk_fwd4Args.kd
    .uniform_work_group_size: 1
    .uses_dynamic_stack: false
    .vgpr_count:     256
    .vgpr_spill_count: 0
    .wavefront_size: 64
